# P7 q/k tiles: all sixteen rope-table loads of the epilogue requested up front (one wait) instead of four serialized load->wait rounds
# speedup vs baseline: 1.0078x; 1.0078x over previous
;     template <int MT> DEVI void operator()(f32x4 (&acc)[MT][4], int row0, int col0, int fr, int fq) const {
;     ...
;             for (int m = 0; m < MT; ++m) {
;                 const int t = t0 + 16 * m + fr;
;                 f32x4 o0 = acc[m][0], o1 = acc[m][1], o2 = acc[m][2], o3 = acc[m][3];
;                 if (!isctx) {
;                     const int pos = t - CTX, prow = pos >> 6, pcol = pos & 63;
;                     const f32x4 cr = *(const f32x4*)(ropec + prow * 16 + 4 * fq), sr = *(const f32x4*)(ropes + prow * 16 + 4 * fq);
;                     const f32x4 cc = *(const f32x4*)(ropec + pcol * 16 + 4 * fq), sc = *(const f32x4*)(ropes + pcol * 16 + 4 * fq);
;                     const f32x4 a0 = o0 * cr - o1 * sr, a1 = o1 * cr + o0 * sr;
;                     const f32x4 a2 = o2 * cc - o3 * sc, a3 = o3 * cc + o2 * sc;
;                     o0 = a0; o1 = a1; o2 = a2; o3 = a3;
;                 }
.LBB0_1343:
	s_andn2_saveexec_b64 s[34:35], s[2:3]
	s_cbranch_execz .LBB0_1334
	v_cmp_lt_i32_e64 s[4:5], s52, v66
	v_cmp_gt_i32_e64 s[2:3], s51, v66
	s_or_b64 s[36:37], s[4:5], vcc
	s_and_saveexec_b64 s[4:5], s[36:37]
	s_cbranch_execz .LBB0_1333
	v_lshlrev_b32_e32 v80, 2, v72
	v_lshlrev_b32_e32 v68, 2, v80
	s_and_saveexec_b64 s[36:37], vcc
	s_cbranch_execz .LBB0_1347
	v_mov_b32_e32 v69, v65
	v_or_b32_e32 v229, v77, v71
	v_mov_b32_e32 v223, v65
	v_mov_b32_e32 v225, v65
	v_add_u32_e32 v222, 0xffffff00, v77
	v_lshlrev_b32_e32 v224, 6, v71
	v_lshl_add_u64 v[226:227], s[6:7], 0, v[222:223]
	v_lshl_add_u64 v[226:227], v[226:227], 0, v[68:69]
	global_load_dwordx4 v[112:115], v[226:227], off
	v_lshl_add_u64 v[226:227], s[0:1], 0, v[222:223]
	v_lshl_add_u64 v[226:227], v[226:227], 0, v[68:69]
	global_load_dwordx4 v[116:119], v[226:227], off
	v_lshl_add_u64 v[226:227], s[6:7], 0, v[224:225]
	v_lshl_add_u64 v[226:227], v[226:227], 0, v[68:69]
	global_load_dwordx4 v[120:123], v[226:227], off
	v_lshl_add_u64 v[226:227], s[0:1], 0, v[224:225]
	v_lshl_add_u64 v[226:227], v[226:227], 0, v[68:69]
	global_load_dwordx4 v[124:127], v[226:227], off
	v_add_u32_e32 v222, 0xffffff10, v77
	v_and_b32_e32 v222, 0xffffffc0, v222
	v_or_b32_e32 v228, 16, v229
	v_lshlrev_b32_e32 v224, 6, v228
	v_and_b32_e32 v224, 0xfc0, v224
	v_lshl_add_u64 v[226:227], s[6:7], 0, v[222:223]
	v_lshl_add_u64 v[226:227], v[226:227], 0, v[68:69]
	global_load_dwordx4 v[128:131], v[226:227], off
	v_lshl_add_u64 v[226:227], s[0:1], 0, v[222:223]
	v_lshl_add_u64 v[226:227], v[226:227], 0, v[68:69]
	global_load_dwordx4 v[132:135], v[226:227], off
	v_lshl_add_u64 v[226:227], s[6:7], 0, v[224:225]
	v_lshl_add_u64 v[226:227], v[226:227], 0, v[68:69]
	global_load_dwordx4 v[136:139], v[226:227], off
	v_lshl_add_u64 v[226:227], s[0:1], 0, v[224:225]
	v_lshl_add_u64 v[226:227], v[226:227], 0, v[68:69]
	global_load_dwordx4 v[140:143], v[226:227], off
	v_add_u32_e32 v222, 0xffffff20, v77
	v_and_b32_e32 v222, 0xffffffc0, v222
	v_or_b32_e32 v228, 32, v229
	v_lshlrev_b32_e32 v224, 6, v228
	v_and_b32_e32 v224, 0xfc0, v224
	v_lshl_add_u64 v[226:227], s[6:7], 0, v[222:223]
	v_lshl_add_u64 v[226:227], v[226:227], 0, v[68:69]
	global_load_dwordx4 v[144:147], v[226:227], off
	v_lshl_add_u64 v[226:227], s[0:1], 0, v[222:223]
	v_lshl_add_u64 v[226:227], v[226:227], 0, v[68:69]
	global_load_dwordx4 v[148:151], v[226:227], off
	v_lshl_add_u64 v[226:227], s[6:7], 0, v[224:225]
	v_lshl_add_u64 v[226:227], v[226:227], 0, v[68:69]
	global_load_dwordx4 v[152:155], v[226:227], off
	v_lshl_add_u64 v[226:227], s[0:1], 0, v[224:225]
	v_lshl_add_u64 v[226:227], v[226:227], 0, v[68:69]
	global_load_dwordx4 v[156:159], v[226:227], off
	v_add_u32_e32 v222, 0xffffff30, v77
	v_and_b32_e32 v222, 0xffffffc0, v222
	v_or_b32_e32 v228, 48, v229
	v_lshlrev_b32_e32 v224, 6, v228
	v_and_b32_e32 v224, 0xfc0, v224
	v_lshl_add_u64 v[226:227], s[6:7], 0, v[222:223]
	v_lshl_add_u64 v[226:227], v[226:227], 0, v[68:69]
	global_load_dwordx4 v[184:187], v[226:227], off
	v_lshl_add_u64 v[226:227], s[0:1], 0, v[222:223]
	v_lshl_add_u64 v[226:227], v[226:227], 0, v[68:69]
	global_load_dwordx4 v[206:209], v[226:227], off
	v_lshl_add_u64 v[226:227], s[6:7], 0, v[224:225]
	v_lshl_add_u64 v[226:227], v[226:227], 0, v[68:69]
	global_load_dwordx4 v[210:213], v[226:227], off
	v_lshl_add_u64 v[226:227], s[0:1], 0, v[224:225]
	v_lshl_add_u64 v[226:227], v[226:227], 0, v[68:69]
	global_load_dwordx4 v[218:221], v[226:227], off
	s_waitcnt vmcnt(0)
	v_add_u32_e32 v64, 0xffffff00, v77
	v_mov_b32_e32 v69, v65
	v_lshl_add_u64 v[72:73], s[6:7], 0, v[64:65]
	v_lshl_add_u64 v[72:73], v[72:73], 0, v[68:69]
	v_lshl_add_u64 v[72:73], s[0:1], 0, v[64:65]
	v_lshl_add_u64 v[72:73], v[72:73], 0, v[68:69]
	v_lshlrev_b32_e32 v64, 6, v71
	v_lshl_add_u64 v[72:73], s[6:7], 0, v[64:65]
	v_lshl_add_u64 v[72:73], v[72:73], 0, v[68:69]
	v_lshl_add_u64 v[72:73], s[0:1], 0, v[64:65]
	v_lshl_add_u64 v[72:73], v[72:73], 0, v[68:69]
	v_pk_mul_f32 v[72:73], v[58:59], v[114:115]
	v_pk_mul_f32 v[78:79], v[56:57], v[112:113]
	v_pk_mul_f32 v[84:85], v[62:63], v[114:115]
	v_pk_mul_f32 v[82:83], v[60:61], v[112:113]
	v_pk_fma_f32 v[62:63], v[62:63], v[118:119], v[72:73] neg_lo:[0,0,1] neg_hi:[0,0,1]
	v_pk_fma_f32 v[60:61], v[60:61], v[116:117], v[78:79] neg_lo:[0,0,1] neg_hi:[0,0,1]
	v_pk_fma_f32 v[58:59], v[58:59], v[118:119], v[84:85]
	v_pk_fma_f32 v[56:57], v[56:57], v[116:117], v[82:83]
	v_pk_mul_f32 v[72:73], v[50:51], v[122:123]
	v_pk_mul_f32 v[78:79], v[48:49], v[120:121]
	v_pk_mul_f32 v[82:83], v[54:55], v[122:123]
	v_pk_mul_f32 v[84:85], v[52:53], v[120:121]
	v_pk_fma_f32 v[54:55], v[54:55], v[126:127], v[72:73] neg_lo:[0,0,1] neg_hi:[0,0,1]
	v_pk_fma_f32 v[52:53], v[52:53], v[124:125], v[78:79] neg_lo:[0,0,1] neg_hi:[0,0,1]
	v_pk_fma_f32 v[50:51], v[50:51], v[126:127], v[82:83]
	v_pk_fma_f32 v[48:49], v[48:49], v[124:125], v[84:85]

; DEVI unsigned pk2(float lo, float hi) { f32x2 v = {lo, hi}; bf16x2_t b = __builtin_convertvector(v, bf16x2_t); return __builtin_bit_cast(unsigned, b); }
;     template <int MT> DEVI void operator()(f32x4 (&acc)[MT][4], int row0, int col0, int fr, int fq) const {
;     ...
;                 f32x4 o0 = acc[m][0], o1 = acc[m][1], o2 = acc[m][2], o3 = acc[m][3];
;                 if (!isctx) {
;                     const int pos = t - CTX, prow = pos >> 6, pcol = pos & 63;
;                     const f32x4 cr = *(const f32x4*)(ropec + prow * 16 + 4 * fq), sr = *(const f32x4*)(ropes + prow * 16 + 4 * fq);
;                     const f32x4 cc = *(const f32x4*)(ropec + pcol * 16 + 4 * fq), sc = *(const f32x4*)(ropes + pcol * 16 + 4 * fq);
;                     const f32x4 a0 = o0 * cr - o1 * sr, a1 = o1 * cr + o0 * sr;
;                     const f32x4 a2 = o2 * cc - o3 * sc, a3 = o3 * cc + o2 * sc;
;                     o0 = a0; o1 = a1; o2 = a2; o3 = a3;
;                 }
;                 bf16_t* dst;
;                 if (isq) {
;                     const float qs = 0.125f * LOG2E;
;                     o0 *= qs; o1 *= qs; o2 *= qs; o3 *= qs;
;                     dst = q + (size_t)(b * SEQ + t - CTX) * 1024 + col0 + 16 * (fq & 1) + 8 * (fq >> 1);
;                 } else {
;                     dst = kbuf + (size_t)(row0 + 16 * m + fr) * 256 + (col0 - 1024) + 16 * (fq & 1) + 8 * (fq >> 1);
;                 }
;                 uint2 x, y;
;                 x.x = pk2(o0[0], o0[1]); x.y = pk2(o0[2], o0[3]); y.x = pk2(o1[0], o1[1]); y.y = pk2(o1[2], o1[3]);
;                 *(uint4*)(dst) = widen16(x, y);
;                 x.x = pk2(o2[0], o2[1]); x.y = pk2(o2[2], o2[3]); y.x = pk2(o3[0], o3[1]); y.y = pk2(o3[2], o3[3]);
;                 *(uint4*)(dst + 32) = widen16(x, y);
.LBB0_1349:
	s_or_saveexec_b64 s[36:37], s[36:37]
	v_or_b32_e32 v74, v74, v71
	v_mov_b32_e32 v64, v66
	s_xor_b64 exec, exec, s[36:37]
	v_ashrrev_i32_e32 v75, 31, v74
	v_lshlrev_b64 v[72:73], 9, v[74:75]
	v_lshl_add_u64 v[72:73], s[54:55], 0, v[72:73]
	v_lshl_add_u64 v[72:73], v[64:65], 1, v[72:73]
	v_lshl_add_u64 v[72:73], v[72:73], 0, s[42:43]
	s_or_b64 exec, exec, s[36:37]
	v_and_b32_e32 v69, 16, v70
	v_and_b32_e32 v75, 8, v80
	v_lshlrev_b32_e32 v70, 1, v69
	v_mov_b32_e32 v71, v65
	v_lshl_add_u64 v[80:81], v[72:73], 0, v[70:71]
	v_lshlrev_b32_e32 v72, 1, v75
	v_mov_b32_e32 v73, v65
	v_cvt_pk_bf16_f32 v60, v60, v61
	v_cvt_pk_bf16_f32 v61, v62, v63
	v_cvt_pk_bf16_f32 v62, v56, v57
	v_cvt_pk_bf16_f32 v63, v58, v59
	v_cvt_pk_bf16_f32 v52, v52, v53
	v_cvt_pk_bf16_f32 v53, v54, v55
	v_cvt_pk_bf16_f32 v54, v48, v49
	v_cvt_pk_bf16_f32 v55, v50, v51
	v_lshl_add_u64 v[80:81], v[80:81], 0, v[72:73]
	v_permlane16_swap_b32_e32 v60, v62
	v_permlane16_swap_b32_e32 v61, v63
	v_permlane16_swap_b32_e32 v52, v54
	v_permlane16_swap_b32_e32 v53, v55
	v_or_b32_e32 v50, 16, v79
	global_store_dwordx4 v[80:81], v[60:63], off
	global_store_dwordx4 v[80:81], v[52:55], off offset:64
	s_and_saveexec_b64 s[36:37], vcc
	s_cbranch_execz .LBB0_1353
	v_add_u32_e32 v48, 0xffffff10, v77
	v_and_b32_e32 v48, 0xffffffc0, v48
	v_mov_b32_e32 v49, v65
	v_lshlrev_b32_e32 v51, 6, v50
	v_mov_b32_e32 v69, v65
	v_lshl_add_u64 v[52:53], s[6:7], 0, v[48:49]
	v_and_b32_e32 v80, 0xfc0, v51
	v_mov_b32_e32 v81, v65
	v_lshl_add_u64 v[48:49], s[0:1], 0, v[48:49]
	v_lshl_add_u64 v[52:53], v[52:53], 0, v[68:69]
	v_lshl_add_u64 v[56:57], s[6:7], 0, v[80:81]
	v_lshl_add_u64 v[48:49], v[48:49], 0, v[68:69]
	v_lshl_add_u64 v[56:57], v[56:57], 0, v[68:69]
	v_lshl_add_u64 v[48:49], s[0:1], 0, v[80:81]
	v_lshl_add_u64 v[48:49], v[48:49], 0, v[68:69]
	v_pk_mul_f32 v[48:49], v[42:43], v[130:131]
	v_pk_mul_f32 v[84:85], v[40:41], v[128:129]
	v_pk_mul_f32 v[54:55], v[46:47], v[130:131]
	v_pk_mul_f32 v[52:53], v[44:45], v[128:129]
	v_pk_mul_f32 v[86:87], v[34:35], v[138:139]
	v_pk_mul_f32 v[88:89], v[32:33], v[136:137]
	v_pk_mul_f32 v[58:59], v[38:39], v[138:139]
	v_pk_mul_f32 v[56:57], v[36:37], v[136:137]
	v_pk_fma_f32 v[46:47], v[46:47], v[134:135], v[48:49] neg_lo:[0,0,1] neg_hi:[0,0,1]
	v_pk_fma_f32 v[44:45], v[44:45], v[132:133], v[84:85] neg_lo:[0,0,1] neg_hi:[0,0,1]
	v_pk_fma_f32 v[42:43], v[42:43], v[134:135], v[54:55]
	v_pk_fma_f32 v[40:41], v[40:41], v[132:133], v[52:53]
	v_pk_fma_f32 v[38:39], v[38:39], v[142:143], v[86:87] neg_lo:[0,0,1] neg_hi:[0,0,1]
	v_pk_fma_f32 v[36:37], v[36:37], v[140:141], v[88:89] neg_lo:[0,0,1] neg_hi:[0,0,1]
	v_pk_fma_f32 v[34:35], v[34:35], v[142:143], v[58:59]
	v_pk_fma_f32 v[32:33], v[32:33], v[140:141], v[56:57]

; DEVI unsigned pk2(float lo, float hi) { f32x2 v = {lo, hi}; bf16x2_t b = __builtin_convertvector(v, bf16x2_t); return __builtin_bit_cast(unsigned, b); }
;     template <int MT> DEVI void operator()(f32x4 (&acc)[MT][4], int row0, int col0, int fr, int fq) const {
;     ...
;                 f32x4 o0 = acc[m][0], o1 = acc[m][1], o2 = acc[m][2], o3 = acc[m][3];
;                 if (!isctx) {
;                     const int pos = t - CTX, prow = pos >> 6, pcol = pos & 63;
;                     const f32x4 cr = *(const f32x4*)(ropec + prow * 16 + 4 * fq), sr = *(const f32x4*)(ropes + prow * 16 + 4 * fq);
;                     const f32x4 cc = *(const f32x4*)(ropec + pcol * 16 + 4 * fq), sc = *(const f32x4*)(ropes + pcol * 16 + 4 * fq);
;                     const f32x4 a0 = o0 * cr - o1 * sr, a1 = o1 * cr + o0 * sr;
;                     const f32x4 a2 = o2 * cc - o3 * sc, a3 = o3 * cc + o2 * sc;
;                     o0 = a0; o1 = a1; o2 = a2; o3 = a3;
;                 }
;                 bf16_t* dst;
;                 if (isq) {
;                     const float qs = 0.125f * LOG2E;
;                     o0 *= qs; o1 *= qs; o2 *= qs; o3 *= qs;
;                     dst = q + (size_t)(b * SEQ + t - CTX) * 1024 + col0 + 16 * (fq & 1) + 8 * (fq >> 1);
;                 } else {
;                     dst = kbuf + (size_t)(row0 + 16 * m + fr) * 256 + (col0 - 1024) + 16 * (fq & 1) + 8 * (fq >> 1);
;                 }
;                 uint2 x, y;
;                 x.x = pk2(o0[0], o0[1]); x.y = pk2(o0[2], o0[3]); y.x = pk2(o1[0], o1[1]); y.y = pk2(o1[2], o1[3]);
;                 *(uint4*)(dst) = widen16(x, y);
;                 x.x = pk2(o2[0], o2[1]); x.y = pk2(o2[2], o2[3]); y.x = pk2(o3[0], o3[1]); y.y = pk2(o3[2], o3[3]);
;                 *(uint4*)(dst + 32) = widen16(x, y);
.LBB0_1357:
	s_or_b64 exec, exec, s[36:37]
	v_mov_b32_e32 v71, v65
	v_lshl_add_u64 v[48:49], v[48:49], 0, v[70:71]
	v_mov_b32_e32 v73, v65
	v_cvt_pk_bf16_f32 v44, v44, v45
	v_cvt_pk_bf16_f32 v45, v46, v47
	v_cvt_pk_bf16_f32 v46, v40, v41
	v_cvt_pk_bf16_f32 v47, v42, v43
	v_cvt_pk_bf16_f32 v36, v36, v37
	v_cvt_pk_bf16_f32 v37, v38, v39
	v_cvt_pk_bf16_f32 v38, v32, v33
	v_cvt_pk_bf16_f32 v39, v34, v35
	v_lshl_add_u64 v[48:49], v[48:49], 0, v[72:73]
	v_permlane16_swap_b32_e32 v44, v46
	v_permlane16_swap_b32_e32 v45, v47
	v_permlane16_swap_b32_e32 v36, v38
	v_permlane16_swap_b32_e32 v37, v39
	v_or_b32_e32 v34, 32, v79
	global_store_dwordx4 v[48:49], v[44:47], off
	global_store_dwordx4 v[48:49], v[36:39], off offset:64
	s_and_saveexec_b64 s[36:37], vcc
	s_cbranch_execz .LBB0_1359
	v_add_u32_e32 v32, 0xffffff20, v77
	v_and_b32_e32 v32, 0xffffffc0, v32
	v_mov_b32_e32 v33, v65
	v_lshlrev_b32_e32 v35, 6, v34
	v_mov_b32_e32 v69, v65
	v_lshl_add_u64 v[36:37], s[6:7], 0, v[32:33]
	v_and_b32_e32 v48, 0xfc0, v35
	v_mov_b32_e32 v49, v65
	v_lshl_add_u64 v[32:33], s[0:1], 0, v[32:33]
	v_lshl_add_u64 v[36:37], v[36:37], 0, v[68:69]
	v_lshl_add_u64 v[40:41], s[6:7], 0, v[48:49]
	v_lshl_add_u64 v[32:33], v[32:33], 0, v[68:69]
	v_lshl_add_u64 v[40:41], v[40:41], 0, v[68:69]
	v_lshl_add_u64 v[32:33], s[0:1], 0, v[48:49]
	v_lshl_add_u64 v[32:33], v[32:33], 0, v[68:69]
	v_pk_mul_f32 v[32:33], v[26:27], v[146:147]
	v_pk_mul_f32 v[52:53], v[24:25], v[144:145]
	v_pk_mul_f32 v[38:39], v[30:31], v[146:147]
	v_pk_mul_f32 v[36:37], v[28:29], v[144:145]
	v_pk_mul_f32 v[54:55], v[18:19], v[154:155]
	v_pk_mul_f32 v[56:57], v[16:17], v[152:153]
	v_pk_mul_f32 v[42:43], v[22:23], v[154:155]
	v_pk_mul_f32 v[40:41], v[20:21], v[152:153]
	v_pk_fma_f32 v[30:31], v[30:31], v[150:151], v[32:33] neg_lo:[0,0,1] neg_hi:[0,0,1]
	v_pk_fma_f32 v[28:29], v[28:29], v[148:149], v[52:53] neg_lo:[0,0,1] neg_hi:[0,0,1]
	v_pk_fma_f32 v[26:27], v[26:27], v[150:151], v[38:39]
	v_pk_fma_f32 v[24:25], v[24:25], v[148:149], v[36:37]
	v_pk_fma_f32 v[22:23], v[22:23], v[158:159], v[54:55] neg_lo:[0,0,1] neg_hi:[0,0,1]
	v_pk_fma_f32 v[20:21], v[20:21], v[156:157], v[56:57] neg_lo:[0,0,1] neg_hi:[0,0,1]
	v_pk_fma_f32 v[18:19], v[18:19], v[158:159], v[42:43]
	v_pk_fma_f32 v[16:17], v[16:17], v[156:157], v[40:41]

; DEVI unsigned pk2(float lo, float hi) { f32x2 v = {lo, hi}; bf16x2_t b = __builtin_convertvector(v, bf16x2_t); return __builtin_bit_cast(unsigned, b); }
;     template <int MT> DEVI void operator()(f32x4 (&acc)[MT][4], int row0, int col0, int fr, int fq) const {
;     ...
;                 f32x4 o0 = acc[m][0], o1 = acc[m][1], o2 = acc[m][2], o3 = acc[m][3];
;                 if (!isctx) {
;                     const int pos = t - CTX, prow = pos >> 6, pcol = pos & 63;
;                     const f32x4 cr = *(const f32x4*)(ropec + prow * 16 + 4 * fq), sr = *(const f32x4*)(ropes + prow * 16 + 4 * fq);
;                     const f32x4 cc = *(const f32x4*)(ropec + pcol * 16 + 4 * fq), sc = *(const f32x4*)(ropes + pcol * 16 + 4 * fq);
;                     const f32x4 a0 = o0 * cr - o1 * sr, a1 = o1 * cr + o0 * sr;
;                     const f32x4 a2 = o2 * cc - o3 * sc, a3 = o3 * cc + o2 * sc;
;                     o0 = a0; o1 = a1; o2 = a2; o3 = a3;
;                 }
;                 bf16_t* dst;
;                 if (isq) {
;                     const float qs = 0.125f * LOG2E;
;                     o0 *= qs; o1 *= qs; o2 *= qs; o3 *= qs;
;                     dst = q + (size_t)(b * SEQ + t - CTX) * 1024 + col0 + 16 * (fq & 1) + 8 * (fq >> 1);
;                 } else {
;                     dst = kbuf + (size_t)(row0 + 16 * m + fr) * 256 + (col0 - 1024) + 16 * (fq & 1) + 8 * (fq >> 1);
;                 }
;                 uint2 x, y;
;                 x.x = pk2(o0[0], o0[1]); x.y = pk2(o0[2], o0[3]); y.x = pk2(o1[0], o1[1]); y.y = pk2(o1[2], o1[3]);
;                 *(uint4*)(dst) = widen16(x, y);
;                 x.x = pk2(o2[0], o2[1]); x.y = pk2(o2[2], o2[3]); y.x = pk2(o3[0], o3[1]); y.y = pk2(o3[2], o3[3]);
;                 *(uint4*)(dst + 32) = widen16(x, y);
.LBB0_1363:
	s_or_b64 exec, exec, s[36:37]
	v_mov_b32_e32 v71, v65
	v_lshl_add_u64 v[32:33], v[32:33], 0, v[70:71]
	v_mov_b32_e32 v73, v65
	v_cvt_pk_bf16_f32 v28, v28, v29
	v_cvt_pk_bf16_f32 v29, v30, v31
	v_cvt_pk_bf16_f32 v30, v24, v25
	v_cvt_pk_bf16_f32 v31, v26, v27
	v_cvt_pk_bf16_f32 v20, v20, v21
	v_cvt_pk_bf16_f32 v21, v22, v23
	v_cvt_pk_bf16_f32 v22, v16, v17
	v_cvt_pk_bf16_f32 v23, v18, v19
	v_lshl_add_u64 v[32:33], v[32:33], 0, v[72:73]
	v_permlane16_swap_b32_e32 v28, v30
	v_permlane16_swap_b32_e32 v29, v31
	v_permlane16_swap_b32_e32 v20, v22
	v_permlane16_swap_b32_e32 v21, v23
	v_or_b32_e32 v18, 48, v79
	global_store_dwordx4 v[32:33], v[28:31], off
	global_store_dwordx4 v[32:33], v[20:23], off offset:64
	s_and_saveexec_b64 s[36:37], vcc
	s_cbranch_execz .LBB0_1365
	v_add_u32_e32 v16, 0xffffff30, v77
	v_and_b32_e32 v16, 0xffffffc0, v16
	v_mov_b32_e32 v17, v65
	v_lshlrev_b32_e32 v19, 6, v18
	v_mov_b32_e32 v69, v65
	v_lshl_add_u64 v[20:21], s[6:7], 0, v[16:17]
	v_and_b32_e32 v32, 0xfc0, v19
	v_mov_b32_e32 v33, v65
	v_lshl_add_u64 v[16:17], s[0:1], 0, v[16:17]
	v_lshl_add_u64 v[20:21], v[20:21], 0, v[68:69]
	v_lshl_add_u64 v[24:25], s[6:7], 0, v[32:33]
	v_lshl_add_u64 v[16:17], v[16:17], 0, v[68:69]
	v_lshl_add_u64 v[24:25], v[24:25], 0, v[68:69]
	v_lshl_add_u64 v[16:17], s[0:1], 0, v[32:33]
	v_lshl_add_u64 v[16:17], v[16:17], 0, v[68:69]
	v_pk_mul_f32 v[16:17], v[10:11], v[186:187]
	v_pk_mul_f32 v[36:37], v[8:9], v[184:185]
	v_pk_mul_f32 v[22:23], v[14:15], v[186:187]
	v_pk_mul_f32 v[20:21], v[12:13], v[184:185]
	v_pk_mul_f32 v[38:39], v[2:3], v[212:213]
	v_pk_mul_f32 v[40:41], v[0:1], v[210:211]
	v_pk_mul_f32 v[26:27], v[6:7], v[212:213]
	v_pk_mul_f32 v[24:25], v[4:5], v[210:211]
	v_pk_fma_f32 v[14:15], v[14:15], v[208:209], v[16:17] neg_lo:[0,0,1] neg_hi:[0,0,1]
	v_pk_fma_f32 v[12:13], v[12:13], v[206:207], v[36:37] neg_lo:[0,0,1] neg_hi:[0,0,1]
	v_pk_fma_f32 v[10:11], v[10:11], v[208:209], v[22:23]
	v_pk_fma_f32 v[8:9], v[8:9], v[206:207], v[20:21]
	v_pk_fma_f32 v[6:7], v[6:7], v[220:221], v[38:39] neg_lo:[0,0,1] neg_hi:[0,0,1]
	v_pk_fma_f32 v[4:5], v[4:5], v[218:219], v[40:41] neg_lo:[0,0,1] neg_hi:[0,0,1]
	v_pk_fma_f32 v[2:3], v[2:3], v[220:221], v[26:27]
	v_pk_fma_f32 v[0:1], v[0:1], v[218:219], v[24:25]
